# P0 absmax passes: wave-to-strip assignment rotated so every wave gets at most 3 strips over the three back-to-back loops (was up to 4, with a sparse last round); on top of v026
# speedup vs baseline: 1.0145x; 1.0118x over previous
; #define BOTH(k) (IN(k) && IN((k) + 1))
; #define GRID_BAR() do { if (N_LAUNCHES != PER_PHASE) xcd_barrier(bar); } while (0)
; template <int ROT>
; __device__ __forceinline__ void gu_absmax(Frame& F, int s_lo, int s_hi) {
;     const int gw = F.vcu * 8 + F.wave, NGW = F.G * 8, lane = (F.tid & 63), kr = lane >> 4, nq = lane & 15;
;     for (int sidx = s_lo + gw; sidx < s_hi; sidx += NGW) {
;         int q, r; if (sidx < GU_STRIPS) { q = sidx / 1376; r = sidx % 1376; } else if (sidx < GU_STRIPS_ALL) { q = 4; r = sidx - GU_STRIPS; } else { q = 5; r = sidx - GU_STRIPS_ALL; }
;         const int nbk = q < 4 ? 172 : 64, kb = r / nbk, nb = r % nbk, rowlen = q < 4 ? FF : DM, ktot = q < 4 ? DM : FF;
;         const float* W = q == 0 ? INP(2) : q == 1 ? INP(3) : q == 2 ? INP(18) : q == 3 ? INP(19) : q == 4 ? INP(20) : INP(4); const float* gain = q < 2 ? INP(1) : (q < 4 ? INP(17) : nullptr);
;         unsigned* cmax = (unsigned*)(F.ws + WS_CTL + CTL_CMAX) + (q < 4 ? (q >> 1) * NGU : 2 * NGU + (q - 4) * DM);
;         const int n = 64 * nb + 4 * nq;
;         const float* src = W + (size_t)(512 * kb + 2 * kr) * rowlen + n;
;         int ntl = (ktot - 512 * kb) / 64; ntl = ntl > 8 ? 8 : ntl;
;         f32x4 cm = (f32x4){0.f, 0.f, 0.f, 0.f};
; #pragma unroll 2
;         for (int t = 0; t < ntl; ++t) {
;             const float gv = gain ? gain[512 * kb + 64 * t + lane] : 1.0f;
; __global__ void __launch_bounds__(512, 2) mk_fwd(Args args) {
;     ...
;     if (IN(0)) { gu_absmax<ROT2>(F, GU_STRIPS, GU_STRIPS_ALL); gu_absmax<ROT1>(F, GU_STRIPS_ALL, GU_STRIPS_ALL + 1408); gu_absmax<0>(F, 2752, GU_STRIPS); GRID_BAR(); p0_prologue(F); if (BOTH(0)) GRID_BAR(); }
.LBB0_46:
	s_mov_b32 s98, s10
	s_cmp_eq_u32 s71, 0x100
	s_cbranch_scc0 .Lmy_bal2
	s_add_i32 s98, s10, 0x580
	s_and_b32 s98, s98, 0x7ff
.Lmy_bal2:
	s_add_i32 s11, s98, 0x1b00
	s_cmpk_gt_i32 s11, 0x207f
	s_cbranch_scc1 .LBB0_91
	v_lshlrev_b32_e32 v2, 2, v0
	v_and_b32_e32 v64, 60, v2
	v_lshrrev_b32_e32 v2, 3, v0
	v_and_b32_e32 v65, 6, v2
	v_mbcnt_lo_u32_b32 v2, -1, 0
	v_mbcnt_hi_u32_b32 v2, -1, v2
	s_waitcnt lgkmcnt(3)
	v_and_b32_e32 v4, 64, v2
	v_xor_b32_e32 v3, 16, v2
	s_waitcnt lgkmcnt(2)
	v_add_u32_e32 v5, 64, v4
	v_cmp_lt_i32_e32 vcc, v3, v5
	s_add_u32 s13, s78, 0x80000
	s_mov_b32 s1, 0
	v_cndmask_b32_e32 v3, v2, v3, vcc
	v_lshlrev_b32_e32 v66, 2, v3
	v_xor_b32_e32 v3, 32, v2
	v_cmp_lt_i32_e32 vcc, v3, v5
	v_cmp_eq_u32_e64 s[2:3], 0, v72
	v_cmp_gt_u32_e64 s[4:5], 16, v1
	v_cndmask_b32_e32 v2, v2, v3, vcc
	v_lshlrev_b32_e32 v67, 2, v2
	v_or_b32_e32 v2, v4, v65
	v_lshlrev_b32_e32 v68, 2, v2
	v_or_b32_e32 v69, 4, v68
	v_or_b32_e32 v70, 32, v68
	v_or_b32_e32 v71, 36, v68
	v_or_b32_e32 v72, 64, v68
	v_or_b32_e32 v73, 0x44, v68
	v_or_b32_e32 v74, 0x60, v68
	v_or_b32_e32 v75, 0x64, v68
	v_or_b32_e32 v76, 0x80, v68
	v_or_b32_e32 v77, 0x84, v68
	v_or_b32_e32 v78, 0xa0, v68
	v_or_b32_e32 v79, 0xa4, v68
	v_or_b32_e32 v80, 0xc0, v68
	v_or_b32_e32 v81, 0xc4, v68
	v_or_b32_e32 v82, 0xe0, v68
	v_or_b32_e32 v83, 0xe4, v68
	s_addc_u32 s20, s79, 0
	s_mov_b32 s21, 0x27c08
	s_movk_i32 s22, 0x1000
	s_mov_b64 s[14:15], 0x100
	v_mov_b32_e32 v84, 0x7c
	s_branch .LBB0_49

; #define BOTH(k) (IN(k) && IN((k) + 1))
; #define GRID_BAR() do { if (N_LAUNCHES != PER_PHASE) xcd_barrier(bar); } while (0)
; template <int ROT>
; __device__ __forceinline__ void gu_absmax(Frame& F, int s_lo, int s_hi) {
;     const int gw = F.vcu * 8 + F.wave, NGW = F.G * 8, lane = (F.tid & 63), kr = lane >> 4, nq = lane & 15;
;     for (int sidx = s_lo + gw; sidx < s_hi; sidx += NGW) {
;         int q, r; if (sidx < GU_STRIPS) { q = sidx / 1376; r = sidx % 1376; } else if (sidx < GU_STRIPS_ALL) { q = 4; r = sidx - GU_STRIPS; } else { q = 5; r = sidx - GU_STRIPS_ALL; }
;         const int nbk = q < 4 ? 172 : 64, kb = r / nbk, nb = r % nbk, rowlen = q < 4 ? FF : DM, ktot = q < 4 ? DM : FF;
;         const float* W = q == 0 ? INP(2) : q == 1 ? INP(3) : q == 2 ? INP(18) : q == 3 ? INP(19) : q == 4 ? INP(20) : INP(4); const float* gain = q < 2 ? INP(1) : (q < 4 ? INP(17) : nullptr);
;         unsigned* cmax = (unsigned*)(F.ws + WS_CTL + CTL_CMAX) + (q < 4 ? (q >> 1) * NGU : 2 * NGU + (q - 4) * DM);
;         const int n = 64 * nb + 4 * nq;
;         const float* src = W + (size_t)(512 * kb + 2 * kr) * rowlen + n;
;         int ntl = (ktot - 512 * kb) / 64; ntl = ntl > 8 ? 8 : ntl;
;         f32x4 cm = (f32x4){0.f, 0.f, 0.f, 0.f};
; #pragma unroll 2
;         for (int t = 0; t < ntl; ++t) {
;             const float gv = gain ? gain[512 * kb + 64 * t + lane] : 1.0f;
; __global__ void __launch_bounds__(512, 2) mk_fwd(Args args) {
;     ...
;     if (IN(0)) { gu_absmax<ROT2>(F, GU_STRIPS, GU_STRIPS_ALL); gu_absmax<ROT1>(F, GU_STRIPS_ALL, GU_STRIPS_ALL + 1408); gu_absmax<0>(F, 2752, GU_STRIPS); GRID_BAR(); p0_prologue(F); if (BOTH(0)) GRID_BAR(); }
.LBB0_91:
	s_mov_b32 s98, s10
	s_cmp_eq_u32 s71, 0x100
	s_cbranch_scc0 .Lmy_bal3
	s_add_i32 s98, s10, 0x280
	s_cmp_lt_u32 s10, 0x280
	s_cselect_b32 s98, s10, s98
	s_add_i32 s99, s10, 0xfffffd00
	s_cmp_gt_u32 s10, 0x57f
	s_cselect_b32 s98, s99, s98
.Lmy_bal3:
	s_add_i32 s8, s98, 0xac0
	s_cmpk_gt_i32 s8, 0x157f
	s_cbranch_scc1 .LBB0_106
	v_lshlrev_b32_e32 v2, 2, v0
	v_and_b32_e32 v75, 60, v2
	v_lshrrev_b32_e32 v2, 3, v0
	v_and_b32_e32 v77, 6, v2
	v_mbcnt_lo_u32_b32 v2, -1, 0
	v_mbcnt_hi_u32_b32 v2, -1, v2
	v_and_b32_e32 v3, 64, v2
	s_waitcnt lgkmcnt(3)
	v_xor_b32_e32 v4, 16, v2
	s_waitcnt lgkmcnt(2)
	v_add_u32_e32 v5, 64, v3
	v_cmp_lt_i32_e32 vcc, v4, v5
	s_add_u32 s9, s78, 0x80000
	v_cmp_gt_u32_e64 s[2:3], 16, v1
	v_cndmask_b32_e32 v4, v2, v4, vcc
	v_lshlrev_b32_e32 v79, 2, v4
	v_xor_b32_e32 v4, 32, v2
	v_cmp_lt_i32_e32 vcc, v4, v5
	s_addc_u32 s11, s79, 0
	v_or_b32_e32 v110, 64, v1
	v_cndmask_b32_e32 v2, v2, v4, vcc
	v_lshlrev_b32_e32 v81, 2, v2
	v_or_b32_e32 v2, v3, v77
	v_lshlrev_b32_e32 v83, 2, v2
	v_or_b32_e32 v85, 4, v83
	v_or_b32_e32 v87, 32, v83
	v_or_b32_e32 v89, 36, v83
	v_or_b32_e32 v91, 64, v83
	v_or_b32_e32 v93, 0x44, v83
	v_or_b32_e32 v95, 0x60, v83
	v_or_b32_e32 v97, 0x64, v83
	v_or_b32_e32 v99, 0x80, v83
	v_or_b32_e32 v101, 0x84, v83
	v_or_b32_e32 v103, 0xa0, v83
	v_or_b32_e32 v105, 0xa4, v83
	v_or_b32_e32 v106, 0xc0, v83
	v_or_b32_e32 v107, 0xc4, v83
	v_or_b32_e32 v108, 0xe0, v83
	v_or_b32_e32 v109, 0xe4, v83
	s_add_i32 s13, 0, 0x27c10
	s_add_i32 s14, 0, 0x27c18
	s_add_i32 s15, 0, 0x27c90
	s_mov_b32 s16, 0x27c98
	s_mov_b32 s17, 0x27c08
	s_mov_b32 s18, 0x2b0000
	s_mov_b32 s19, 0x2ba000
	s_mov_b32 s20, 0x306000
	s_mov_b32 s21, 0x310000
	s_mov_b32 s22, 0x35c000
	s_mov_b32 s23, 0x366000
	s_mov_b32 s24, 0x3b2000
	s_mov_b32 s25, 0x3bc000
	s_mov_b32 s26, 0x408000
	s_mov_b32 s27, 0x412000
	s_mov_b32 s28, 0x45e000
	s_mov_b32 s29, 0x468000
	s_mov_b32 s30, 0x4b4000
	s_mov_b32 s31, 0x4be000
	s_mov_b32 s33, 0x50a000
	s_mov_b32 s35, 0x514000
	s_mov_b64 s[0:1], 0x200
	v_mov_b32_e32 v111, 0x7c
	s_branch .LBB0_94
